# mixer phase 2 (scan + neighbourhood attention MFMA loops): one static s_setprio 1 for waves 4-7 at phase entry, reset at phase exit
# speedup vs baseline: 1.0046x; 1.0046x over previous
; template <int DK> __device__ __forceinline__ void p2_load(P2Frag<DK>& f, const ScanBufs<DK>& S, int dir, int g, int h, int dkb, int dvb, int r, int hi) {
;     const bf16* kt = S.KT + (((((size_t)dir * NCH + g) * 8 + h) * 8 + hi) * DK + dkb * 32 + r) * 8;
;     const bf16* vt = S.VT + ((((size_t)g * 8 + h) * 8 + hi) * 128 + dvb * 64 + r) * 8;
;     const float* ae = S.AE + (((size_t)dir * NCH + g) * 8 + h) * DK + dkb * 32 + 4 * hi;
; #pragma unroll
;     for (int kk = 0; kk < 4; ++kk) { f.a[kk] = *(const GAS bf16x8*)(kt + (size_t)kk * 2 * DK * 8); f.bv[0][kk] = *(const GAS bf16x8*)(vt + (size_t)kk * 2 * 128 * 8); f.bv[1][kk] = *(const GAS bf16x8*)(vt + (size_t)kk * 2 * 128 * 8 + 32 * 8); f.ae[kk] = *(const GAS f32x4*)(ae + 8 * kk); }
; }
; template <int DK> __device__ __forceinline__ void scan_state_unit(const ScanBufs<DK>& S, int unit, int lane, bool skip_ctx_store) {
;     constexpr int NKB = DK / 32;
;     const int dvb = unit & 1, dkb = (unit >> 1) % NKB, rest = (unit >> 1) / NKB; const int dir = rest & 1, h = (rest >> 1) & 7, b = rest >> 4;
;     const int r = lane & 31, hi = lane >> 5;
;     f32x16 acc[2]; acc[0] = f32x16{}; acc[1] = f32x16{};
;     P2Frag<DK> cur, nxt; p2_load<DK>(cur, S, dir, scan_chunk(b, dir, 0), h, dkb, dvb, r, hi);
;     for (int s = 0; s < 36; ++s) {
;         const int g = scan_chunk(b, dir, s);
;         if (s + 1 < 36) p2_load<DK>(nxt, S, dir, scan_chunk(b, dir, s + 1), h, dkb, dvb, r, hi);
;         if (!(skip_ctx_store && s < 4)) {
;             bf16* sp = S.SP + (((((size_t)dir * NCH + g) * 8 + h) * (DK / 8) + dkb * 4) * 128 + dvb * 64 + r) * 8 + 4 * hi;
; #pragma unroll
;             for (int j = 0; j < 2; ++j)
; #pragma unroll
;                 for (int q = 0; q < 4; ++q) { v2u o; o.x = pk2(acc[j][4 * q], acc[j][4 * q + 1]); o.y = pk2(acc[j][4 * q + 2], acc[j][4 * q + 3]); *(GAS v2u*)(sp + ((size_t)q * 128 + j * 32) * 8) = o; }
; __device__ __forceinline__ void mixer_phase2(Frame& FF, int l, int rep) {
;     Frame F = FF; F.lane = xb_lane(); F.tid = F.wave * 64 + F.lane; const int lane = F.lane, tid = F.tid;
;     { const ScanBufs<128> A = bufsA(F.ws); const ScanBufs<64> B = bufsB(F.ws);
;       const int gw = F.vcu * NWAVES + F.wave; const bool lastl = (l == DEPTH - 1);
;       if (gw < 512) scan_state_unit<128>(A, gw, lane, lastl);
;       else if (gw < 768) scan_state_unit<64>(B, gw - 512, lane, lastl); }
.LBB0_904:
	s_andn2_b64 vcc, exec, s[0:1]
	s_cbranch_vccnz .LBB0_1080
	v_readlane_b32 s100, v251, 40
	s_nop 0
	s_bitcmp1_b32 s100, 10
	s_cbranch_scc0 .Lprio2_skip
	s_setprio 1
.Lprio2_skip:
	v_mov_b32_e32 v0, v65
	v_readlane_b32 s0, v250, 0
	v_mbcnt_lo_u32_b32 v0, -1, v0
	v_mbcnt_hi_u32_b32 v192, -1, v0
	v_readlane_b32 s1, v250, 1
	v_and_b32_e32 v208, 31, v192
	s_and_b64 vcc, exec, s[0:1]
	s_cbranch_vccz .LBB0_918
	v_readlane_b32 s0, v250, 2
	v_readlane_b32 s1, v250, 3
	s_mov_b64 s[4:5], 0
	s_and_b64 vcc, exec, s[0:1]
	s_mov_b64 s[0:1], 0
	s_cbranch_vccz .LBB0_919
	v_ashrrev_i32_e32 v0, 5, v192
	v_ashrrev_i32_e32 v1, 31, v0
	v_readlane_b32 s0, v250, 5
	s_waitcnt vmcnt(0)
	v_lshlrev_b64 v[16:17], 6, v[0:1]
	v_readlane_b32 s1, v250, 6
	v_lshlrev_b32_e32 v182, 2, v0
	v_ashrrev_i32_e32 v183, 31, v182
	v_lshl_add_u64 v[2:3], v[16:17], 0, s[0:1]
	v_readlane_b32 s0, v250, 26
	v_or_b32_e32 v2, v2, v208
	v_readlane_b32 s1, v250, 27
	v_readlane_b32 s2, v250, 10
	v_lshlrev_b64 v[18:19], 2, v[182:183]
	v_lshl_add_u64 v[8:9], v[2:3], 4, s[0:1]
	v_readlane_b32 s0, v245, 4
	v_lshlrev_b64 v[2:3], 7, v[0:1]
	v_readlane_b32 s1, v245, 5
	v_readlane_b32 s3, v250, 11
	s_nop 0
	v_lshl_add_u64 v[180:181], v[2:3], 0, s[0:1]
	v_readlane_b32 s0, v250, 8
	v_readlane_b32 s1, v250, 9
	v_lshl_add_u64 v[12:13], s[2:3], 0, v[18:19]
	s_movk_i32 s2, 0x2000
	v_lshl_add_u64 v[2:3], v[180:181], 0, s[0:1]
	v_readlane_b32 s0, v250, 41
	v_or_b32_e32 v2, v2, v208
	v_readlane_b32 s1, v250, 42
	s_nop 1
	v_lshl_add_u64 v[10:11], v[2:3], 4, s[0:1]
	v_add_co_u32_e32 v14, vcc, s67, v10
	global_load_dwordx4 v[40:43], v[10:11], off
	global_load_dwordx4 v[32:35], v[10:11], off offset:512
	global_load_dwordx4 v[36:39], v[8:9], off
	global_load_dwordx4 v[44:47], v[8:9], off offset:2048
	v_addc_co_u32_e32 v15, vcc, 0, v11, vcc
	v_add_co_u32_e32 v20, vcc, s2, v10
	s_movk_i32 s2, 0x3000
	s_nop 0
	v_addc_co_u32_e32 v21, vcc, 0, v11, vcc
	v_add_co_u32_e32 v8, vcc, s67, v8
	global_load_dwordx4 v[0:3], v[12:13], off
	global_load_dwordx4 v[4:7], v[12:13], off offset:32
	v_addc_co_u32_e32 v9, vcc, 0, v9, vcc
	v_add_co_u32_e32 v22, vcc, s2, v10
	v_readlane_b32 s2, v250, 4
	s_nop 0
	v_addc_co_u32_e32 v23, vcc, 0, v11, vcc
	v_or_b32_e32 v24, s2, v208
	v_readlane_b32 s2, v250, 7
	v_or_b32_e32 v16, v24, v16
	v_lshlrev_b64 v[184:185], 4, v[16:17]
	v_or_b32_e32 v178, s2, v208
	v_readlane_b32 s2, v250, 12
	v_readlane_b32 s3, v250, 13
	global_load_dwordx4 v[48:51], v[14:15], off offset:512
	global_load_dwordx4 v[86:89], v[8:9], off
	global_load_dwordx4 v[94:97], v[20:21], off
	global_load_dwordx4 v[98:101], v[20:21], off offset:512
	v_lshl_add_u64 v[16:17], s[2:3], 0, v[184:185]
	v_readlane_b32 s2, v250, 14
	v_readlane_b32 s3, v250, 15
	global_load_dwordx4 v[106:109], v[8:9], off offset:2048
	global_load_dwordx4 v[110:113], v[22:23], off
	s_nop 0
	global_load_dwordx4 v[8:11], v[12:13], off offset:64
	s_nop 0
	global_load_dwordx4 v[12:15], v[12:13], off offset:96
	v_lshl_add_u64 v[24:25], v[180:181], 0, s[2:3]
	v_or_b32_e32 v24, v178, v24
	v_lshl_add_u64 v[24:25], v[24:25], 4, s[0:1]
	v_readlane_b32 s0, v250, 16
	v_readlane_b32 s1, v250, 17
	s_nop 1
	v_lshl_add_u64 v[18:19], s[0:1], 0, v[18:19]
	global_load_dwordx4 v[126:129], v[22:23], off offset:512
	global_load_dwordx4 v[52:55], v[16:17], off
	global_load_dwordx4 v[56:59], v[24:25], off offset:512
	global_load_dwordx4 v[78:81], v[18:19], off
	global_load_dwordx4 v[118:121], v[24:25], off
	global_load_dwordx4 v[60:63], v[16:17], off offset:2048
	v_add_co_u32_e32 v22, vcc, 0x1000, v24
	v_readlane_b32 s0, v245, 54
	s_nop 0
	v_addc_co_u32_e32 v23, vcc, 0, v25, vcc
	v_add_co_u32_e32 v16, vcc, 0x1000, v16
	v_readlane_b32 s1, v245, 55
	s_nop 0
	v_addc_co_u32_e32 v17, vcc, 0, v17, vcc
	v_add_co_u32_e32 v26, vcc, 0x2000, v24
	global_load_dwordx4 v[66:69], v[22:23], off offset:512
	global_load_dwordx4 v[70:73], v[16:17], off
	v_addc_co_u32_e32 v27, vcc, 0, v25, vcc
	global_load_dwordx4 v[130:133], v[18:19], off offset:32
	global_load_dwordx4 v[142:145], v[18:19], off offset:64
	global_load_dwordx4 v[82:85], v[26:27], off
	global_load_dwordx4 v[74:77], v[16:17], off offset:2048
	v_add_co_u32_e32 v16, vcc, 0x3000, v24
	s_nop 1
	v_addc_co_u32_e32 v17, vcc, 0, v25, vcc
	global_load_dwordx4 v[90:93], v[26:27], off offset:512
	global_load_dwordx4 v[102:105], v[16:17], off
	global_load_dwordx4 v[134:137], v[20:21], off offset:-4096
	global_load_dwordx4 v[114:117], v[16:17], off offset:512
	global_load_dwordx4 v[122:125], v[22:23], off
	global_load_dwordx4 v[154:157], v[18:19], off offset:96
	v_cndmask_b32_e64 v16, 0, 1, s[0:1]
	v_cmp_ne_u32_e64 s[2:3], 1, v16
	s_andn2_b64 vcc, exec, s[0:1]
	s_cbranch_vccnz .LBB0_909
	v_readlane_b32 s0, v250, 18
	s_mov_b32 s76, s77
	v_mov_b64_e32 v[20:21], s[76:77]
	v_or_b32_e32 v64, s0, v178
	v_readlane_b32 s0, v249, 62
	v_readlane_b32 s1, v249, 63
	s_nop 1
	v_lshl_add_u64 v[16:17], v[64:65], 4, s[0:1]
	v_lshl_add_u64 v[16:17], v[182:183], 1, v[16:17]
	v_add_co_u32_e32 v18, vcc, 0x1000, v16
	global_store_dwordx2 v[16:17], v[20:21], off
	global_store_dwordx2 v[16:17], v[20:21], off offset:2048
	v_addc_co_u32_e32 v19, vcc, 0, v17, vcc
	global_store_dwordx2 v[18:19], v[20:21], off
	global_store_dwordx2 v[18:19], v[20:21], off offset:2048
	global_store_dwordx2 v[16:17], v[20:21], off offset:512
	global_store_dwordx2 v[16:17], v[20:21], off offset:2560
	global_store_dwordx2 v[18:19], v[20:21], off offset:512
	global_store_dwordx2 v[18:19], v[20:21], off offset:2560

; #define RUN(kind, ...) do { _Pragma("nounroll") for (int rep_ = 0; rep_ < ((REP_KIND == (kind)) ? 2 : 1); ++rep_) { __VA_ARGS__; } } while (0)
; #define SEAM(k) do { if (IN((k) + 1)) { if (use_bar) { xcd_barrier(bar); if (REP_KIND == 9) xcd_barrier(bar); } else if (F.tid == 0) __hip_atomic_store(F.ctl + CW_TMO, 0xBADBA0u, RLX_AGENT); } } while (0)
; __global__ void __launch_bounds__(NWAVES * 64, 2) fwd_kernel(Args args) {
;     ...
;         if (IN(pb + 2)) { mixer_phase2(F, l, 0); if (REP_KIND == 3) mixer_phase2(F, l, 1); SEAM(pb + 2); }
;         if (IN(pb + 3)) { RUN(4, mixer_phase3(F, l)); SEAM(pb + 3); }
.LBB0_1080:
	s_setprio 0
	v_readlane_b32 s0, v248, 0
	v_readlane_b32 s1, v248, 1
	s_mov_b64 s[4:5], s[0:1]
	s_cmp_le_i32 s4, s16
	v_readlane_b32 s2, v248, 2
	v_readlane_b32 s3, v248, 3
	s_cselect_b64 s[0:1], -1, 0
	s_cmp_lt_i32 s16, s5
	s_cselect_b64 s[2:3], -1, 0
	s_and_b64 s[2:3], s[0:1], s[2:3]
	s_mov_b64 s[0:1], -1
	s_and_b64 vcc, exec, s[2:3]
	s_cbranch_vccnz .LBB0_1082
	v_readlane_b32 s0, v245, 49
	s_add_i32 s16, s0, 7
	s_mov_b64 s[0:1], 0
